# residual-add epilogues keep sixteen reads of x in flight (ring over the fragment registers that are dead in the epilogue)
# speedup vs baseline: 1.2518x; 1.0000x over previous
.LBB0_1015:
	v_lshl_add_u32 v150, s51, 8, v143
	v_lshl_or_b32 v148, s52, 8, v153
	v_ashrrev_i32_e32 v151, 31, v150
	v_ashrrev_i32_e32 v149, 31, v148
	v_lshlrev_b64 v[140:141], 10, v[150:151]
	v_lshl_add_u64 v[140:141], v[140:141], 0, v[148:149]
	v_lshl_add_u64 v[140:141], v[140:141], 2, s[18:19]
	s_mov_b64 s[0:1], 0x10000
	v_lshl_add_u64 v[236:237], v[140:141], 0, s[0:1]
	s_mov_b64 s[0:1], 0x20000
	v_lshl_add_u64 v[238:239], v[140:141], 0, s[0:1]
	s_mov_b64 s[0:1], 0x30000
	v_lshl_add_u64 v[240:241], v[140:141], 0, s[0:1]
	s_mov_b64 s[0:1], 0x80000
	v_lshl_add_u64 v[242:243], v[140:141], 0, s[0:1]
	s_mov_b64 s[0:1], 0x90000
	v_lshl_add_u64 v[244:245], v[140:141], 0, s[0:1]
	s_mov_b64 s[0:1], 0xa0000
	v_lshl_add_u64 v[246:247], v[140:141], 0, s[0:1]
	s_mov_b64 s[0:1], 0xb0000
	v_lshl_add_u64 v[248:249], v[140:141], 0, s[0:1]
	global_load_dwordx4 v[156:159], v[140:141], off offset:0
	global_load_dwordx4 v[160:163], v[140:141], off offset:16
	global_load_dwordx4 v[164:167], v[140:141], off offset:512
	global_load_dwordx4 v[168:171], v[140:141], off offset:528
	global_load_dwordx4 v[172:175], v[236:237], off offset:0
	global_load_dwordx4 v[176:179], v[236:237], off offset:16
	global_load_dwordx4 v[180:183], v[236:237], off offset:512
	global_load_dwordx4 v[184:187], v[236:237], off offset:528
	global_load_dwordx4 v[188:191], v[238:239], off offset:0
	global_load_dwordx4 v[192:195], v[238:239], off offset:16
	global_load_dwordx4 v[196:199], v[238:239], off offset:512
	global_load_dwordx4 v[200:203], v[238:239], off offset:528
	global_load_dwordx4 v[204:207], v[240:241], off offset:0
	global_load_dwordx4 v[220:223], v[240:241], off offset:16
	global_load_dwordx4 v[224:227], v[240:241], off offset:512
	global_load_dwordx4 v[228:231], v[240:241], off offset:528
	s_waitcnt vmcnt(15)
	v_pk_add_f32 v[128:129], v[128:129], v[158:159]
	v_pk_add_f32 v[126:127], v[126:127], v[156:157]
	global_store_dwordx4 v[140:141], v[126:129], off offset:0
	global_load_dwordx4 v[156:159], v[242:243], off offset:0
	s_waitcnt vmcnt(16)
	v_pk_add_f32 v[124:125], v[124:125], v[162:163]
	v_pk_add_f32 v[122:123], v[122:123], v[160:161]
	global_store_dwordx4 v[140:141], v[122:125], off offset:16
	global_load_dwordx4 v[160:163], v[242:243], off offset:16
	s_waitcnt vmcnt(17)
	v_pk_add_f32 v[120:121], v[120:121], v[166:167]
	v_pk_add_f32 v[118:119], v[118:119], v[164:165]
	global_store_dwordx4 v[140:141], v[118:121], off offset:512
	global_load_dwordx4 v[164:167], v[242:243], off offset:512
	s_waitcnt vmcnt(18)
	v_pk_add_f32 v[116:117], v[116:117], v[170:171]
	v_pk_add_f32 v[114:115], v[114:115], v[168:169]
	global_store_dwordx4 v[140:141], v[114:117], off offset:528
	global_load_dwordx4 v[168:171], v[242:243], off offset:528
	s_waitcnt vmcnt(19)
	v_pk_add_f32 v[112:113], v[112:113], v[174:175]
	v_pk_add_f32 v[110:111], v[110:111], v[172:173]
	global_store_dwordx4 v[236:237], v[110:113], off offset:0
	global_load_dwordx4 v[172:175], v[244:245], off offset:0
	s_waitcnt vmcnt(20)
	v_pk_add_f32 v[108:109], v[108:109], v[178:179]
	v_pk_add_f32 v[106:107], v[106:107], v[176:177]
	global_store_dwordx4 v[236:237], v[106:109], off offset:16
	global_load_dwordx4 v[176:179], v[244:245], off offset:16
	s_waitcnt vmcnt(21)
	v_pk_add_f32 v[104:105], v[104:105], v[182:183]
	v_pk_add_f32 v[102:103], v[102:103], v[180:181]
	global_store_dwordx4 v[236:237], v[102:105], off offset:512
	global_load_dwordx4 v[180:183], v[244:245], off offset:512
	s_waitcnt vmcnt(22)
	v_pk_add_f32 v[100:101], v[100:101], v[186:187]
	v_pk_add_f32 v[98:99], v[98:99], v[184:185]
	global_store_dwordx4 v[236:237], v[98:101], off offset:528
	global_load_dwordx4 v[184:187], v[244:245], off offset:528
	s_waitcnt vmcnt(23)
	v_pk_add_f32 v[96:97], v[96:97], v[190:191]
	v_pk_add_f32 v[94:95], v[94:95], v[188:189]
	global_store_dwordx4 v[238:239], v[94:97], off offset:0
	global_load_dwordx4 v[188:191], v[246:247], off offset:0
	s_waitcnt vmcnt(24)
	v_pk_add_f32 v[92:93], v[92:93], v[194:195]
	v_pk_add_f32 v[90:91], v[90:91], v[192:193]
	global_store_dwordx4 v[238:239], v[90:93], off offset:16
	global_load_dwordx4 v[192:195], v[246:247], off offset:16
	s_waitcnt vmcnt(25)
	v_pk_add_f32 v[88:89], v[88:89], v[198:199]
	v_pk_add_f32 v[86:87], v[86:87], v[196:197]
	global_store_dwordx4 v[238:239], v[86:89], off offset:512
	global_load_dwordx4 v[196:199], v[246:247], off offset:512
	s_waitcnt vmcnt(26)
	v_pk_add_f32 v[84:85], v[84:85], v[202:203]
	v_pk_add_f32 v[82:83], v[82:83], v[200:201]
	global_store_dwordx4 v[238:239], v[82:85], off offset:528
	global_load_dwordx4 v[200:203], v[246:247], off offset:528
	s_waitcnt vmcnt(27)
	v_pk_add_f32 v[80:81], v[80:81], v[206:207]
	v_pk_add_f32 v[78:79], v[78:79], v[204:205]
	global_store_dwordx4 v[240:241], v[78:81], off offset:0
	global_load_dwordx4 v[204:207], v[248:249], off offset:0
	s_waitcnt vmcnt(28)
	v_pk_add_f32 v[76:77], v[76:77], v[222:223]
	v_pk_add_f32 v[74:75], v[74:75], v[220:221]
	global_store_dwordx4 v[240:241], v[74:77], off offset:16
	global_load_dwordx4 v[220:223], v[248:249], off offset:16
	s_waitcnt vmcnt(29)
	v_pk_add_f32 v[72:73], v[72:73], v[226:227]
	v_pk_add_f32 v[70:71], v[70:71], v[224:225]
	global_store_dwordx4 v[240:241], v[70:73], off offset:512
	global_load_dwordx4 v[224:227], v[248:249], off offset:512
	s_waitcnt vmcnt(30)
	v_pk_add_f32 v[68:69], v[68:69], v[230:231]
	v_pk_add_f32 v[66:67], v[66:67], v[228:229]
	global_store_dwordx4 v[240:241], v[66:69], off offset:528
	global_load_dwordx4 v[228:231], v[248:249], off offset:528
	s_waitcnt vmcnt(30)
	v_pk_add_f32 v[62:63], v[62:63], v[158:159]
	v_pk_add_f32 v[60:61], v[60:61], v[156:157]
	global_store_dwordx4 v[242:243], v[60:63], off offset:0
	s_waitcnt vmcnt(29)
	v_pk_add_f32 v[58:59], v[58:59], v[162:163]
	v_pk_add_f32 v[56:57], v[56:57], v[160:161]
	global_store_dwordx4 v[242:243], v[56:59], off offset:16
	s_waitcnt vmcnt(28)
	v_pk_add_f32 v[54:55], v[54:55], v[166:167]
	v_pk_add_f32 v[52:53], v[52:53], v[164:165]
	global_store_dwordx4 v[242:243], v[52:55], off offset:512
	s_waitcnt vmcnt(27)
	v_pk_add_f32 v[50:51], v[50:51], v[170:171]
	v_pk_add_f32 v[48:49], v[48:49], v[168:169]
	global_store_dwordx4 v[242:243], v[48:51], off offset:528
	s_waitcnt vmcnt(26)
	v_pk_add_f32 v[46:47], v[46:47], v[174:175]
	v_pk_add_f32 v[44:45], v[44:45], v[172:173]
	global_store_dwordx4 v[244:245], v[44:47], off offset:0
	s_waitcnt vmcnt(25)
	v_pk_add_f32 v[42:43], v[42:43], v[178:179]
	v_pk_add_f32 v[40:41], v[40:41], v[176:177]
	global_store_dwordx4 v[244:245], v[40:43], off offset:16
	s_waitcnt vmcnt(24)
	v_pk_add_f32 v[38:39], v[38:39], v[182:183]
	v_pk_add_f32 v[36:37], v[36:37], v[180:181]
	global_store_dwordx4 v[244:245], v[36:39], off offset:512
	s_waitcnt vmcnt(23)
	v_pk_add_f32 v[34:35], v[34:35], v[186:187]
	v_pk_add_f32 v[32:33], v[32:33], v[184:185]
	global_store_dwordx4 v[244:245], v[32:35], off offset:528
	s_waitcnt vmcnt(22)
	v_pk_add_f32 v[30:31], v[30:31], v[190:191]
	v_pk_add_f32 v[28:29], v[28:29], v[188:189]
	global_store_dwordx4 v[246:247], v[28:31], off offset:0
	s_waitcnt vmcnt(21)
	v_pk_add_f32 v[26:27], v[26:27], v[194:195]
	v_pk_add_f32 v[24:25], v[24:25], v[192:193]
	global_store_dwordx4 v[246:247], v[24:27], off offset:16
	s_waitcnt vmcnt(20)
	v_pk_add_f32 v[22:23], v[22:23], v[198:199]
	v_pk_add_f32 v[20:21], v[20:21], v[196:197]
	global_store_dwordx4 v[246:247], v[20:23], off offset:512
	s_waitcnt vmcnt(19)
	v_pk_add_f32 v[18:19], v[18:19], v[202:203]
	v_pk_add_f32 v[16:17], v[16:17], v[200:201]
	global_store_dwordx4 v[246:247], v[16:19], off offset:528
	s_waitcnt vmcnt(18)
	v_pk_add_f32 v[14:15], v[14:15], v[206:207]
	v_pk_add_f32 v[12:13], v[12:13], v[204:205]
	global_store_dwordx4 v[248:249], v[12:15], off offset:0
	s_waitcnt vmcnt(17)
	v_pk_add_f32 v[10:11], v[10:11], v[222:223]
	v_pk_add_f32 v[8:9], v[8:9], v[220:221]
	global_store_dwordx4 v[248:249], v[8:11], off offset:16
	s_waitcnt vmcnt(16)
	v_pk_add_f32 v[6:7], v[6:7], v[226:227]
	v_pk_add_f32 v[4:5], v[4:5], v[224:225]
	global_store_dwordx4 v[248:249], v[4:7], off offset:512
	s_waitcnt vmcnt(15)
	v_pk_add_f32 v[2:3], v[2:3], v[230:231]
	v_pk_add_f32 v[0:1], v[0:1], v[228:229]
	global_store_dwordx4 v[248:249], v[0:3], off offset:528
	s_mov_b64 s[0:1], -1
	s_and_b64 vcc, exec, s[8:9]
	s_cbranch_vccnz .LBB0_1000
	s_andn2_b64 vcc, exec, s[16:17]
	s_cbranch_vccnz .LBB0_999
	s_barrier
	s_branch .LBB0_999

.LBB0_1356:
	v_lshl_add_u32 v150, s24, 8, v143
	v_lshl_or_b32 v148, s50, 8, v153
	v_ashrrev_i32_e32 v151, 31, v150
	v_ashrrev_i32_e32 v149, 31, v148
	v_lshlrev_b64 v[140:141], 10, v[150:151]
	v_lshl_add_u64 v[140:141], v[140:141], 0, v[148:149]
	v_lshlrev_b64 v[140:141], 2, v[140:141]
	v_lshl_add_u64 v[160:161], s[12:13], 0, v[140:141]
	v_add_u32_e32 v236, 0x10000, v140
	v_add_u32_e32 v237, 0x20000, v140
	v_add_u32_e32 v238, 0x30000, v140
	v_add_u32_e32 v239, 0x80000, v140
	v_add_u32_e32 v240, 0x90000, v140
	v_add_u32_e32 v241, 0xa0000, v140
	v_add_u32_e32 v242, 0xb0000, v140
	global_load_dwordx4 v[156:159], v140, s[12:13] offset:0
	global_load_dwordx4 v[160:163], v140, s[12:13] offset:16
	global_load_dwordx4 v[164:167], v140, s[12:13] offset:512
	global_load_dwordx4 v[168:171], v140, s[12:13] offset:528
	global_load_dwordx4 v[172:175], v236, s[12:13] offset:0
	global_load_dwordx4 v[176:179], v236, s[12:13] offset:16
	global_load_dwordx4 v[180:183], v236, s[12:13] offset:512
	global_load_dwordx4 v[184:187], v236, s[12:13] offset:528
	global_load_dwordx4 v[188:191], v237, s[12:13] offset:0
	global_load_dwordx4 v[192:195], v237, s[12:13] offset:16
	global_load_dwordx4 v[196:199], v237, s[12:13] offset:512
	global_load_dwordx4 v[200:203], v237, s[12:13] offset:528
	global_load_dwordx4 v[204:207], v238, s[12:13] offset:0
	global_load_dwordx4 v[220:223], v238, s[12:13] offset:16
	global_load_dwordx4 v[224:227], v238, s[12:13] offset:512
	global_load_dwordx4 v[228:231], v238, s[12:13] offset:528
	s_waitcnt vmcnt(15)
	v_pk_add_f32 v[128:129], v[128:129], v[158:159]
	v_pk_add_f32 v[126:127], v[126:127], v[156:157]
	global_store_dwordx4 v140, v[126:129], s[40:41] offset:0
	global_load_dwordx4 v[156:159], v239, s[12:13] offset:0
	s_waitcnt vmcnt(16)
	v_pk_add_f32 v[124:125], v[124:125], v[162:163]
	v_pk_add_f32 v[122:123], v[122:123], v[160:161]
	global_store_dwordx4 v140, v[122:125], s[40:41] offset:16
	global_load_dwordx4 v[160:163], v239, s[12:13] offset:16
	s_waitcnt vmcnt(17)
	v_pk_add_f32 v[120:121], v[120:121], v[166:167]
	v_pk_add_f32 v[118:119], v[118:119], v[164:165]
	global_store_dwordx4 v140, v[118:121], s[40:41] offset:512
	global_load_dwordx4 v[164:167], v239, s[12:13] offset:512
	s_waitcnt vmcnt(18)
	v_pk_add_f32 v[116:117], v[116:117], v[170:171]
	v_pk_add_f32 v[114:115], v[114:115], v[168:169]
	global_store_dwordx4 v140, v[114:117], s[40:41] offset:528
	global_load_dwordx4 v[168:171], v239, s[12:13] offset:528
	s_waitcnt vmcnt(19)
	v_pk_add_f32 v[112:113], v[112:113], v[174:175]
	v_pk_add_f32 v[110:111], v[110:111], v[172:173]
	global_store_dwordx4 v236, v[110:113], s[40:41] offset:0
	global_load_dwordx4 v[172:175], v240, s[12:13] offset:0
	s_waitcnt vmcnt(20)
	v_pk_add_f32 v[108:109], v[108:109], v[178:179]
	v_pk_add_f32 v[106:107], v[106:107], v[176:177]
	global_store_dwordx4 v236, v[106:109], s[40:41] offset:16
	global_load_dwordx4 v[176:179], v240, s[12:13] offset:16
	s_waitcnt vmcnt(21)
	v_pk_add_f32 v[104:105], v[104:105], v[182:183]
	v_pk_add_f32 v[102:103], v[102:103], v[180:181]
	global_store_dwordx4 v236, v[102:105], s[40:41] offset:512
	global_load_dwordx4 v[180:183], v240, s[12:13] offset:512
	s_waitcnt vmcnt(22)
	v_pk_add_f32 v[100:101], v[100:101], v[186:187]
	v_pk_add_f32 v[98:99], v[98:99], v[184:185]
	global_store_dwordx4 v236, v[98:101], s[40:41] offset:528
	global_load_dwordx4 v[184:187], v240, s[12:13] offset:528
	s_waitcnt vmcnt(23)
	v_pk_add_f32 v[96:97], v[96:97], v[190:191]
	v_pk_add_f32 v[94:95], v[94:95], v[188:189]
	global_store_dwordx4 v237, v[94:97], s[40:41] offset:0
	global_load_dwordx4 v[188:191], v241, s[12:13] offset:0
	s_waitcnt vmcnt(24)
	v_pk_add_f32 v[92:93], v[92:93], v[194:195]
	v_pk_add_f32 v[90:91], v[90:91], v[192:193]
	global_store_dwordx4 v237, v[90:93], s[40:41] offset:16
	global_load_dwordx4 v[192:195], v241, s[12:13] offset:16
	s_waitcnt vmcnt(25)
	v_pk_add_f32 v[88:89], v[88:89], v[198:199]
	v_pk_add_f32 v[86:87], v[86:87], v[196:197]
	global_store_dwordx4 v237, v[86:89], s[40:41] offset:512
	global_load_dwordx4 v[196:199], v241, s[12:13] offset:512
	s_waitcnt vmcnt(26)
	v_pk_add_f32 v[84:85], v[84:85], v[202:203]
	v_pk_add_f32 v[82:83], v[82:83], v[200:201]
	global_store_dwordx4 v237, v[82:85], s[40:41] offset:528
	global_load_dwordx4 v[200:203], v241, s[12:13] offset:528
	s_waitcnt vmcnt(27)
	v_pk_add_f32 v[80:81], v[80:81], v[206:207]
	v_pk_add_f32 v[78:79], v[78:79], v[204:205]
	global_store_dwordx4 v238, v[78:81], s[40:41] offset:0
	global_load_dwordx4 v[204:207], v242, s[12:13] offset:0
	s_waitcnt vmcnt(28)
	v_pk_add_f32 v[76:77], v[76:77], v[222:223]
	v_pk_add_f32 v[74:75], v[74:75], v[220:221]
	global_store_dwordx4 v238, v[74:77], s[40:41] offset:16
	global_load_dwordx4 v[220:223], v242, s[12:13] offset:16
	s_waitcnt vmcnt(29)
	v_pk_add_f32 v[72:73], v[72:73], v[226:227]
	v_pk_add_f32 v[70:71], v[70:71], v[224:225]
	global_store_dwordx4 v238, v[70:73], s[40:41] offset:512
	global_load_dwordx4 v[224:227], v242, s[12:13] offset:512
	s_waitcnt vmcnt(30)
	v_pk_add_f32 v[68:69], v[68:69], v[230:231]
	v_pk_add_f32 v[66:67], v[66:67], v[228:229]
	global_store_dwordx4 v238, v[66:69], s[40:41] offset:528
	global_load_dwordx4 v[228:231], v242, s[12:13] offset:528
	s_waitcnt vmcnt(30)
	v_pk_add_f32 v[62:63], v[62:63], v[158:159]
	v_pk_add_f32 v[60:61], v[60:61], v[156:157]
	global_store_dwordx4 v239, v[60:63], s[40:41] offset:0
	s_waitcnt vmcnt(29)
	v_pk_add_f32 v[58:59], v[58:59], v[162:163]
	v_pk_add_f32 v[56:57], v[56:57], v[160:161]
	global_store_dwordx4 v239, v[56:59], s[40:41] offset:16
	s_waitcnt vmcnt(28)
	v_pk_add_f32 v[54:55], v[54:55], v[166:167]
	v_pk_add_f32 v[52:53], v[52:53], v[164:165]
	global_store_dwordx4 v239, v[52:55], s[40:41] offset:512
	s_waitcnt vmcnt(27)
	v_pk_add_f32 v[50:51], v[50:51], v[170:171]
	v_pk_add_f32 v[48:49], v[48:49], v[168:169]
	global_store_dwordx4 v239, v[48:51], s[40:41] offset:528
	s_waitcnt vmcnt(26)
	v_pk_add_f32 v[46:47], v[46:47], v[174:175]
	v_pk_add_f32 v[44:45], v[44:45], v[172:173]
	global_store_dwordx4 v240, v[44:47], s[40:41] offset:0
	s_waitcnt vmcnt(25)
	v_pk_add_f32 v[42:43], v[42:43], v[178:179]
	v_pk_add_f32 v[40:41], v[40:41], v[176:177]
	global_store_dwordx4 v240, v[40:43], s[40:41] offset:16
	s_waitcnt vmcnt(24)
	v_pk_add_f32 v[38:39], v[38:39], v[182:183]
	v_pk_add_f32 v[36:37], v[36:37], v[180:181]
	global_store_dwordx4 v240, v[36:39], s[40:41] offset:512
	s_waitcnt vmcnt(23)
	v_pk_add_f32 v[34:35], v[34:35], v[186:187]
	v_pk_add_f32 v[32:33], v[32:33], v[184:185]
	global_store_dwordx4 v240, v[32:35], s[40:41] offset:528
	s_waitcnt vmcnt(22)
	v_pk_add_f32 v[30:31], v[30:31], v[190:191]
	v_pk_add_f32 v[28:29], v[28:29], v[188:189]
	global_store_dwordx4 v241, v[28:31], s[40:41] offset:0
	s_waitcnt vmcnt(21)
	v_pk_add_f32 v[26:27], v[26:27], v[194:195]
	v_pk_add_f32 v[24:25], v[24:25], v[192:193]
	global_store_dwordx4 v241, v[24:27], s[40:41] offset:16
	s_waitcnt vmcnt(20)
	v_pk_add_f32 v[22:23], v[22:23], v[198:199]
	v_pk_add_f32 v[20:21], v[20:21], v[196:197]
	global_store_dwordx4 v241, v[20:23], s[40:41] offset:512
	s_waitcnt vmcnt(19)
	v_pk_add_f32 v[18:19], v[18:19], v[202:203]
	v_pk_add_f32 v[16:17], v[16:17], v[200:201]
	global_store_dwordx4 v241, v[16:19], s[40:41] offset:528
	s_waitcnt vmcnt(18)
	v_pk_add_f32 v[14:15], v[14:15], v[206:207]
	v_pk_add_f32 v[12:13], v[12:13], v[204:205]
	global_store_dwordx4 v242, v[12:15], s[40:41] offset:0
	s_waitcnt vmcnt(17)
	v_pk_add_f32 v[10:11], v[10:11], v[222:223]
	v_pk_add_f32 v[8:9], v[8:9], v[220:221]
	global_store_dwordx4 v242, v[8:11], s[40:41] offset:16
	s_waitcnt vmcnt(16)
	v_pk_add_f32 v[6:7], v[6:7], v[226:227]
	v_pk_add_f32 v[4:5], v[4:5], v[224:225]
	global_store_dwordx4 v242, v[4:7], s[40:41] offset:512
	s_waitcnt vmcnt(15)
	v_pk_add_f32 v[2:3], v[2:3], v[230:231]
	v_pk_add_f32 v[0:1], v[0:1], v[228:229]
	global_store_dwordx4 v242, v[0:3], s[40:41] offset:528
	s_mov_b64 s[0:1], -1
	s_andn2_b64 vcc, exec, s[8:9]
	s_cbranch_vccnz .LBB0_1345
	s_andn2_b64 vcc, exec, s[10:11]
	s_cbranch_vccnz .LBB0_1344
	s_barrier
	s_branch .LBB0_1344

.LBB0_1582:
	v_lshl_add_u32 v150, s37, 8, v143
	v_lshl_or_b32 v140, s38, 8, v153
	v_ashrrev_i32_e32 v151, 31, v150
	v_ashrrev_i32_e32 v141, 31, v140
	v_lshlrev_b64 v[144:145], 12, v[150:151]
	v_lshl_add_u64 v[144:145], s[40:41], 0, v[144:145]
	v_lshlrev_b64 v[148:149], 2, v[140:141]
	v_lshl_add_u64 v[140:141], v[144:145], 0, v[148:149]
	s_mov_b64 s[0:1], 0x10000
	v_lshl_add_u64 v[236:237], v[140:141], 0, s[0:1]
	s_mov_b64 s[0:1], 0x20000
	v_lshl_add_u64 v[238:239], v[140:141], 0, s[0:1]
	s_mov_b64 s[0:1], 0x30000
	v_lshl_add_u64 v[240:241], v[140:141], 0, s[0:1]
	s_mov_b64 s[0:1], 0x80000
	v_lshl_add_u64 v[242:243], v[140:141], 0, s[0:1]
	s_mov_b64 s[0:1], 0x90000
	v_lshl_add_u64 v[244:245], v[140:141], 0, s[0:1]
	s_mov_b64 s[0:1], 0xa0000
	v_lshl_add_u64 v[246:247], v[140:141], 0, s[0:1]
	s_mov_b64 s[0:1], 0xb0000
	v_lshl_add_u64 v[248:249], v[140:141], 0, s[0:1]
	global_load_dwordx4 v[156:159], v[140:141], off offset:0
	global_load_dwordx4 v[160:163], v[140:141], off offset:16
	global_load_dwordx4 v[164:167], v[140:141], off offset:512
	global_load_dwordx4 v[168:171], v[140:141], off offset:528
	global_load_dwordx4 v[172:175], v[236:237], off offset:0
	global_load_dwordx4 v[176:179], v[236:237], off offset:16
	global_load_dwordx4 v[180:183], v[236:237], off offset:512
	global_load_dwordx4 v[184:187], v[236:237], off offset:528
	global_load_dwordx4 v[188:191], v[238:239], off offset:0
	global_load_dwordx4 v[192:195], v[238:239], off offset:16
	global_load_dwordx4 v[196:199], v[238:239], off offset:512
	global_load_dwordx4 v[200:203], v[238:239], off offset:528
	global_load_dwordx4 v[204:207], v[240:241], off offset:0
	global_load_dwordx4 v[220:223], v[240:241], off offset:16
	global_load_dwordx4 v[224:227], v[240:241], off offset:512
	global_load_dwordx4 v[228:231], v[240:241], off offset:528
	s_waitcnt vmcnt(15)
	v_pk_add_f32 v[128:129], v[128:129], v[158:159]
	v_pk_add_f32 v[126:127], v[126:127], v[156:157]
	global_store_dwordx4 v[140:141], v[126:129], off offset:0
	global_load_dwordx4 v[156:159], v[242:243], off offset:0
	s_waitcnt vmcnt(16)
	v_pk_add_f32 v[124:125], v[124:125], v[162:163]
	v_pk_add_f32 v[122:123], v[122:123], v[160:161]
	global_store_dwordx4 v[140:141], v[122:125], off offset:16
	global_load_dwordx4 v[160:163], v[242:243], off offset:16
	s_waitcnt vmcnt(17)
	v_pk_add_f32 v[120:121], v[120:121], v[166:167]
	v_pk_add_f32 v[118:119], v[118:119], v[164:165]
	global_store_dwordx4 v[140:141], v[118:121], off offset:512
	global_load_dwordx4 v[164:167], v[242:243], off offset:512
	s_waitcnt vmcnt(18)
	v_pk_add_f32 v[116:117], v[116:117], v[170:171]
	v_pk_add_f32 v[114:115], v[114:115], v[168:169]
	global_store_dwordx4 v[140:141], v[114:117], off offset:528
	global_load_dwordx4 v[168:171], v[242:243], off offset:528
	s_waitcnt vmcnt(19)
	v_pk_add_f32 v[112:113], v[112:113], v[174:175]
	v_pk_add_f32 v[110:111], v[110:111], v[172:173]
	global_store_dwordx4 v[236:237], v[110:113], off offset:0
	global_load_dwordx4 v[172:175], v[244:245], off offset:0
	s_waitcnt vmcnt(20)
	v_pk_add_f32 v[108:109], v[108:109], v[178:179]
	v_pk_add_f32 v[106:107], v[106:107], v[176:177]
	global_store_dwordx4 v[236:237], v[106:109], off offset:16
	global_load_dwordx4 v[176:179], v[244:245], off offset:16
	s_waitcnt vmcnt(21)
	v_pk_add_f32 v[104:105], v[104:105], v[182:183]
	v_pk_add_f32 v[102:103], v[102:103], v[180:181]
	global_store_dwordx4 v[236:237], v[102:105], off offset:512
	global_load_dwordx4 v[180:183], v[244:245], off offset:512
	s_waitcnt vmcnt(22)
	v_pk_add_f32 v[100:101], v[100:101], v[186:187]
	v_pk_add_f32 v[98:99], v[98:99], v[184:185]
	global_store_dwordx4 v[236:237], v[98:101], off offset:528
	global_load_dwordx4 v[184:187], v[244:245], off offset:528
	s_waitcnt vmcnt(23)
	v_pk_add_f32 v[96:97], v[96:97], v[190:191]
	v_pk_add_f32 v[94:95], v[94:95], v[188:189]
	global_store_dwordx4 v[238:239], v[94:97], off offset:0
	global_load_dwordx4 v[188:191], v[246:247], off offset:0
	s_waitcnt vmcnt(24)
	v_pk_add_f32 v[92:93], v[92:93], v[194:195]
	v_pk_add_f32 v[90:91], v[90:91], v[192:193]
	global_store_dwordx4 v[238:239], v[90:93], off offset:16
	global_load_dwordx4 v[192:195], v[246:247], off offset:16
	s_waitcnt vmcnt(25)
	v_pk_add_f32 v[88:89], v[88:89], v[198:199]
	v_pk_add_f32 v[86:87], v[86:87], v[196:197]
	global_store_dwordx4 v[238:239], v[86:89], off offset:512
	global_load_dwordx4 v[196:199], v[246:247], off offset:512
	s_waitcnt vmcnt(26)
	v_pk_add_f32 v[84:85], v[84:85], v[202:203]
	v_pk_add_f32 v[82:83], v[82:83], v[200:201]
	global_store_dwordx4 v[238:239], v[82:85], off offset:528
	global_load_dwordx4 v[200:203], v[246:247], off offset:528
	s_waitcnt vmcnt(27)
	v_pk_add_f32 v[80:81], v[80:81], v[206:207]
	v_pk_add_f32 v[78:79], v[78:79], v[204:205]
	global_store_dwordx4 v[240:241], v[78:81], off offset:0
	global_load_dwordx4 v[204:207], v[248:249], off offset:0
	s_waitcnt vmcnt(28)
	v_pk_add_f32 v[76:77], v[76:77], v[222:223]
	v_pk_add_f32 v[74:75], v[74:75], v[220:221]
	global_store_dwordx4 v[240:241], v[74:77], off offset:16
	global_load_dwordx4 v[220:223], v[248:249], off offset:16
	s_waitcnt vmcnt(29)
	v_pk_add_f32 v[72:73], v[72:73], v[226:227]
	v_pk_add_f32 v[70:71], v[70:71], v[224:225]
	global_store_dwordx4 v[240:241], v[70:73], off offset:512
	global_load_dwordx4 v[224:227], v[248:249], off offset:512
	s_waitcnt vmcnt(30)
	v_pk_add_f32 v[68:69], v[68:69], v[230:231]
	v_pk_add_f32 v[66:67], v[66:67], v[228:229]
	global_store_dwordx4 v[240:241], v[66:69], off offset:528
	global_load_dwordx4 v[228:231], v[248:249], off offset:528
	s_waitcnt vmcnt(30)
	v_pk_add_f32 v[62:63], v[62:63], v[158:159]
	v_pk_add_f32 v[60:61], v[60:61], v[156:157]
	global_store_dwordx4 v[242:243], v[60:63], off offset:0
	s_waitcnt vmcnt(29)
	v_pk_add_f32 v[58:59], v[58:59], v[162:163]
	v_pk_add_f32 v[56:57], v[56:57], v[160:161]
	global_store_dwordx4 v[242:243], v[56:59], off offset:16
	s_waitcnt vmcnt(28)
	v_pk_add_f32 v[54:55], v[54:55], v[166:167]
	v_pk_add_f32 v[52:53], v[52:53], v[164:165]
	global_store_dwordx4 v[242:243], v[52:55], off offset:512
	s_waitcnt vmcnt(27)
	v_pk_add_f32 v[50:51], v[50:51], v[170:171]
	v_pk_add_f32 v[48:49], v[48:49], v[168:169]
	global_store_dwordx4 v[242:243], v[48:51], off offset:528
	s_waitcnt vmcnt(26)
	v_pk_add_f32 v[46:47], v[46:47], v[174:175]
	v_pk_add_f32 v[44:45], v[44:45], v[172:173]
	global_store_dwordx4 v[244:245], v[44:47], off offset:0
	s_waitcnt vmcnt(25)
	v_pk_add_f32 v[42:43], v[42:43], v[178:179]
	v_pk_add_f32 v[40:41], v[40:41], v[176:177]
	global_store_dwordx4 v[244:245], v[40:43], off offset:16
	s_waitcnt vmcnt(24)
	v_pk_add_f32 v[38:39], v[38:39], v[182:183]
	v_pk_add_f32 v[36:37], v[36:37], v[180:181]
	global_store_dwordx4 v[244:245], v[36:39], off offset:512
	s_waitcnt vmcnt(23)
	v_pk_add_f32 v[34:35], v[34:35], v[186:187]
	v_pk_add_f32 v[32:33], v[32:33], v[184:185]
	global_store_dwordx4 v[244:245], v[32:35], off offset:528
	s_waitcnt vmcnt(22)
	v_pk_add_f32 v[30:31], v[30:31], v[190:191]
	v_pk_add_f32 v[28:29], v[28:29], v[188:189]
	global_store_dwordx4 v[246:247], v[28:31], off offset:0
	s_waitcnt vmcnt(21)
	v_pk_add_f32 v[26:27], v[26:27], v[194:195]
	v_pk_add_f32 v[24:25], v[24:25], v[192:193]
	global_store_dwordx4 v[246:247], v[24:27], off offset:16
	s_waitcnt vmcnt(20)
	v_pk_add_f32 v[22:23], v[22:23], v[198:199]
	v_pk_add_f32 v[20:21], v[20:21], v[196:197]
	global_store_dwordx4 v[246:247], v[20:23], off offset:512
	s_waitcnt vmcnt(19)
	v_pk_add_f32 v[18:19], v[18:19], v[202:203]
	v_pk_add_f32 v[16:17], v[16:17], v[200:201]
	global_store_dwordx4 v[246:247], v[16:19], off offset:528
	s_waitcnt vmcnt(18)
	v_pk_add_f32 v[14:15], v[14:15], v[206:207]
	v_pk_add_f32 v[12:13], v[12:13], v[204:205]
	global_store_dwordx4 v[248:249], v[12:15], off offset:0
	s_waitcnt vmcnt(17)
	v_pk_add_f32 v[10:11], v[10:11], v[222:223]
	v_pk_add_f32 v[8:9], v[8:9], v[220:221]
	global_store_dwordx4 v[248:249], v[8:11], off offset:16
	s_waitcnt vmcnt(16)
	v_pk_add_f32 v[6:7], v[6:7], v[226:227]
	v_pk_add_f32 v[4:5], v[4:5], v[224:225]
	global_store_dwordx4 v[248:249], v[4:7], off offset:512
	s_waitcnt vmcnt(15)
	v_pk_add_f32 v[2:3], v[2:3], v[230:231]
	v_pk_add_f32 v[0:1], v[0:1], v[228:229]
	global_store_dwordx4 v[248:249], v[0:3], off offset:528
	s_mov_b64 s[0:1], -1
	s_and_b64 vcc, exec, s[8:9]
	s_cbranch_vccnz .LBB0_1567
	s_andn2_b64 vcc, exec, s[12:13]
	s_cbranch_vccnz .LBB0_1566
	s_barrier
	s_branch .LBB0_1566
